# NSA sel+win loops: max3 tree + permlane32_swap reduce, on top of diff-attn permlane reduce
# speedup vs baseline: 1.0262x; 1.0126x over previous
.LBB0_405:
	v_max3_f32 v169, v18, v19, v20
	v_max3_f32 v171, v21, v22, v23
	v_max3_f32 v172, v24, v25, v26
	v_max3_f32 v169, v169, v27, v28
	v_max3_f32 v171, v171, v29, v30
	v_max3_f32 v172, v172, v31, v32
	v_max3_f32 v169, v169, v171, v33
	v_max_f32_e32 v169, v169, v172
	v_max3_f32 v171, v2, v3, v4
	v_max3_f32 v172, v5, v6, v7
	v_max3_f32 v173, v8, v9, v10
	v_max3_f32 v171, v171, v11, v12
	v_max3_f32 v172, v172, v13, v14
	v_max3_f32 v173, v173, v15, v16
	v_max3_f32 v171, v171, v172, v17
	v_max3_f32 v169, v169, v171, v173
	v_cndmask_b32_e64 v169, v222, v169, s[40:41]
	v_mov_b32_e32 v171, v169
	s_nop 1
	v_permlane32_swap_b32_e32 v169, v171
	v_max3_f32 v169, v170, v169, v171
	v_cmp_gt_f32_e32 vcc, v169, v170
	s_cbranch_vccz .LBB0_407
	v_sub_f32_e32 v170, v170, v169
	v_mul_f32_e32 v170, 0x3e38aa3b, v170
	v_exp_f32_e32 v170, v170
	s_nop 0
	v_mul_f32_e32 v201, v201, v170
	v_pk_mul_f32 v[80:81], v[80:81], v[170:171] op_sel_hi:[1,0]
	v_pk_mul_f32 v[78:79], v[78:79], v[170:171] op_sel_hi:[1,0]
	v_pk_mul_f32 v[76:77], v[76:77], v[170:171] op_sel_hi:[1,0]
	v_pk_mul_f32 v[74:75], v[74:75], v[170:171] op_sel_hi:[1,0]
	v_pk_mul_f32 v[72:73], v[72:73], v[170:171] op_sel_hi:[1,0]
	v_pk_mul_f32 v[70:71], v[70:71], v[170:171] op_sel_hi:[1,0]
	v_pk_mul_f32 v[68:69], v[68:69], v[170:171] op_sel_hi:[1,0]
	v_pk_mul_f32 v[66:67], v[66:67], v[170:171] op_sel_hi:[1,0]
	v_pk_mul_f32 v[96:97], v[96:97], v[170:171] op_sel_hi:[1,0]
	v_pk_mul_f32 v[94:95], v[94:95], v[170:171] op_sel_hi:[1,0]
	v_pk_mul_f32 v[92:93], v[92:93], v[170:171] op_sel_hi:[1,0]
	v_pk_mul_f32 v[90:91], v[90:91], v[170:171] op_sel_hi:[1,0]
	v_pk_mul_f32 v[88:89], v[88:89], v[170:171] op_sel_hi:[1,0]
	v_pk_mul_f32 v[86:87], v[86:87], v[170:171] op_sel_hi:[1,0]
	v_pk_mul_f32 v[84:85], v[84:85], v[170:171] op_sel_hi:[1,0]
	v_pk_mul_f32 v[82:83], v[82:83], v[170:171] op_sel_hi:[1,0]

.LBB0_416:
	v_max3_f32 v0, v114, v115, v116
	v_max3_f32 v194, v117, v118, v119
	v_max3_f32 v195, v120, v121, v122
	v_max3_f32 v0, v0, v123, v124
	v_max3_f32 v194, v194, v125, v126
	v_max3_f32 v195, v195, v127, v128
	v_max3_f32 v0, v0, v194, v129
	v_max_f32_e32 v0, v0, v195
	v_max3_f32 v194, v98, v99, v100
	v_max3_f32 v195, v101, v102, v103
	v_max3_f32 v196, v104, v105, v106
	v_max3_f32 v194, v194, v107, v108
	v_max3_f32 v195, v195, v109, v110
	v_max3_f32 v196, v196, v111, v112
	v_max3_f32 v194, v194, v195, v113
	v_max3_f32 v0, v0, v194, v196
	v_mov_b32_e32 v194, v0
	s_nop 1
	v_permlane32_swap_b32_e32 v0, v194
	v_max3_f32 v0, v242, v0, v194
	v_cmp_gt_f32_e32 vcc, v0, v242
	s_cbranch_vccz .LBB0_418
	v_sub_f32_e32 v194, v242, v0
	v_mul_f32_e32 v194, 0x3e38aa3b, v194
	v_exp_f32_e32 v194, v194
	s_nop 0
	v_mul_f32_e32 v203, v203, v194
	v_pk_mul_f32 v[32:33], v[32:33], v[194:195] op_sel_hi:[1,0]
	v_pk_mul_f32 v[30:31], v[30:31], v[194:195] op_sel_hi:[1,0]
	v_pk_mul_f32 v[28:29], v[28:29], v[194:195] op_sel_hi:[1,0]
	v_pk_mul_f32 v[26:27], v[26:27], v[194:195] op_sel_hi:[1,0]
	v_pk_mul_f32 v[24:25], v[24:25], v[194:195] op_sel_hi:[1,0]
	v_pk_mul_f32 v[22:23], v[22:23], v[194:195] op_sel_hi:[1,0]
	v_pk_mul_f32 v[20:21], v[20:21], v[194:195] op_sel_hi:[1,0]
	v_pk_mul_f32 v[18:19], v[18:19], v[194:195] op_sel_hi:[1,0]
	v_pk_mul_f32 v[16:17], v[16:17], v[194:195] op_sel_hi:[1,0]
	v_pk_mul_f32 v[14:15], v[14:15], v[194:195] op_sel_hi:[1,0]
	v_pk_mul_f32 v[12:13], v[12:13], v[194:195] op_sel_hi:[1,0]
	v_pk_mul_f32 v[10:11], v[10:11], v[194:195] op_sel_hi:[1,0]
	v_pk_mul_f32 v[8:9], v[8:9], v[194:195] op_sel_hi:[1,0]
	v_pk_mul_f32 v[6:7], v[6:7], v[194:195] op_sel_hi:[1,0]
	v_pk_mul_f32 v[4:5], v[4:5], v[194:195] op_sel_hi:[1,0]
	v_pk_mul_f32 v[2:3], v[2:3], v[194:195] op_sel_hi:[1,0]
